# P0a w_in transposes: decode (it&63, it>>6): a 2048-item round writes whole 8-KB output rows instead of a 1-KB column band of every row, on p0map
# speedup vs baseline: 1.0087x; 1.0026x over previous
.LBB0_77:
	s_andn2_b64 vcc, exec, s[6:7]
	s_cbranch_vccnz .LBB0_11
	s_and_b32 s6, s4, 63
	s_waitcnt lgkmcnt(0)
	s_load_dwordx2 s[10:11], s[12:13], 0x40
	s_lshr_b32 s7, s4, 6
	s_lshl_b32 s8, s6, 6
	s_lshl_b32 s6, s7, 5
	s_cmpk_gt_i32 s7, 0xbf
	s_mov_b64 s[26:27], -1
	v_or_b32_e32 v3, s8, v1
	v_or_b32_e32 v2, s8, v38
	s_cbranch_scc0 .LBB0_82
	s_mov_b32 s7, s17
	s_lshl_b64 s[26:27], s[6:7], 2
	s_waitcnt lgkmcnt(0)
	s_add_u32 s26, s10, s26
	s_addc_u32 s27, s11, s27
	v_mov_b32_e32 v61, v35
	v_lshl_add_u64 v[4:5], s[26:27], 0, v[60:61]
	s_mov_b32 s7, 1
	s_mov_b32 s9, 0
	s_mov_b32 s16, 32
